# v108 plus the now-empty lgkmcnt(0) waits after the permlane row-max exchange removed in the attention loops
# speedup vs baseline: 1.0051x; 1.0051x over previous
.LBB0_685:
	v_lshl_or_b32 v0, s38, 5, v202
	v_mad_u32_u24 v0, v0, s30, v208
	ds_read_b128 v[2:5], v0
	ds_read_b128 v[6:9], v0 offset:32
	ds_read_b128 v[222:225], v0 offset:64
	ds_read_b128 v[226:229], v0 offset:96
	ds_read_b128 v[230:233], v0 offset:128
	ds_read_b128 v[234:237], v0 offset:160
	s_waitcnt lgkmcnt(5)
	v_mfma_f32_32x32x16_bf16 v[80:95], v[2:5], v[148:151], 0
	ds_read_b128 v[2:5], v0 offset:192
	s_waitcnt lgkmcnt(5)
	v_mfma_f32_32x32x16_bf16 v[80:95], v[6:9], v[96:99], v[80:95]
	ds_read_b128 v[6:9], v0 offset:224
	s_waitcnt lgkmcnt(5)
	v_mfma_f32_32x32x16_bf16 v[80:95], v[222:225], v[100:103], v[80:95]
	ds_read_b128 v[222:225], v0 offset:256
	s_waitcnt lgkmcnt(5)
	v_mfma_f32_32x32x16_bf16 v[80:95], v[226:229], v[104:107], v[80:95]
	ds_read_b128 v[226:229], v0 offset:288
	s_waitcnt lgkmcnt(5)
	v_mfma_f32_32x32x16_bf16 v[80:95], v[230:233], v[108:111], v[80:95]
	ds_read_b128 v[230:233], v0 offset:320
	s_waitcnt lgkmcnt(5)
	v_mfma_f32_32x32x16_bf16 v[80:95], v[234:237], v[112:115], v[80:95]
	ds_read_b128 v[234:237], v0 offset:352
	s_waitcnt lgkmcnt(5)
	v_mfma_f32_32x32x16_bf16 v[80:95], v[2:5], v[116:119], v[80:95]
	s_waitcnt lgkmcnt(4)
	v_mfma_f32_32x32x16_bf16 v[80:95], v[6:9], v[120:123], v[80:95]
	s_waitcnt lgkmcnt(3)
	v_mfma_f32_32x32x16_bf16 v[80:95], v[222:225], v[124:127], v[80:95]
	s_waitcnt lgkmcnt(2)
	v_mfma_f32_32x32x16_bf16 v[80:95], v[226:229], v[128:131], v[80:95]
	s_waitcnt lgkmcnt(1)
	v_mfma_f32_32x32x16_bf16 v[80:95], v[230:233], v[132:135], v[80:95]
	s_waitcnt lgkmcnt(0)
	v_mfma_f32_32x32x16_bf16 v[80:95], v[234:237], v[140:143], v[80:95]
	s_nop 11
	v_max_f32_e32 v0, v80, v81
	v_max3_f32 v0, v0, v82, v83
	v_max3_f32 v0, v0, v84, v85
	v_max3_f32 v0, v0, v86, v87
	v_max3_f32 v0, v0, v88, v89
	v_max3_f32 v0, v0, v90, v91
	v_max3_f32 v0, v0, v92, v93
	v_max3_f32 v0, v0, v94, v95
	v_mov_b32_e32 v2, v0
	s_nop 1
	v_permlane32_swap_b32_e32 v2, v0
	v_max_f32_e32 v0, v0, v2
	v_mul_f32_e32 v0, 0x3dd53b94, v0
	v_add_f32_e32 v250, 0xc1000000, v0
	v_cmp_gt_f32_e32 vcc, v250, v198
	s_cbranch_vccz .LBB0_684
	v_max_f32_e32 v0, v0, v0
	v_max_f32_e32 v2, v198, v198
	v_max_f32_e32 v2, v2, v0
	v_sub_f32_e32 v0, v198, v2
	v_exp_f32_e32 v0, v0
	v_mov_b32_e32 v198, v2
	v_pk_mul_f32 v[78:79], v[78:79], v[0:1] op_sel_hi:[1,0]
	v_pk_mul_f32 v[76:77], v[76:77], v[0:1] op_sel_hi:[1,0]
	v_pk_mul_f32 v[74:75], v[74:75], v[0:1] op_sel_hi:[1,0]
	v_pk_mul_f32 v[72:73], v[72:73], v[0:1] op_sel_hi:[1,0]
	v_pk_mul_f32 v[70:71], v[70:71], v[0:1] op_sel_hi:[1,0]
	v_pk_mul_f32 v[68:69], v[68:69], v[0:1] op_sel_hi:[1,0]
	v_pk_mul_f32 v[66:67], v[66:67], v[0:1] op_sel_hi:[1,0]
	v_pk_mul_f32 v[64:65], v[64:65], v[0:1] op_sel_hi:[1,0]
	v_pk_mul_f32 v[62:63], v[62:63], v[0:1] op_sel_hi:[1,0]
	v_pk_mul_f32 v[60:61], v[60:61], v[0:1] op_sel_hi:[1,0]
	v_pk_mul_f32 v[58:59], v[58:59], v[0:1] op_sel_hi:[1,0]
	v_pk_mul_f32 v[56:57], v[56:57], v[0:1] op_sel_hi:[1,0]
	v_pk_mul_f32 v[54:55], v[54:55], v[0:1] op_sel_hi:[1,0]
	v_pk_mul_f32 v[52:53], v[52:53], v[0:1] op_sel_hi:[1,0]
	v_pk_mul_f32 v[50:51], v[50:51], v[0:1] op_sel_hi:[1,0]
	v_pk_mul_f32 v[48:49], v[48:49], v[0:1] op_sel_hi:[1,0]
	v_pk_mul_f32 v[46:47], v[46:47], v[0:1] op_sel_hi:[1,0]
	v_pk_mul_f32 v[44:45], v[44:45], v[0:1] op_sel_hi:[1,0]
	v_pk_mul_f32 v[42:43], v[42:43], v[0:1] op_sel_hi:[1,0]
	v_pk_mul_f32 v[40:41], v[40:41], v[0:1] op_sel_hi:[1,0]
	v_pk_mul_f32 v[38:39], v[38:39], v[0:1] op_sel_hi:[1,0]
	v_pk_mul_f32 v[36:37], v[36:37], v[0:1] op_sel_hi:[1,0]
	v_pk_mul_f32 v[34:35], v[34:35], v[0:1] op_sel_hi:[1,0]
	v_pk_mul_f32 v[32:33], v[32:33], v[0:1] op_sel_hi:[1,0]
	v_pk_mul_f32 v[30:31], v[30:31], v[0:1] op_sel_hi:[1,0]
	v_pk_mul_f32 v[28:29], v[28:29], v[0:1] op_sel_hi:[1,0]
	v_pk_mul_f32 v[26:27], v[26:27], v[0:1] op_sel_hi:[1,0]
	v_pk_mul_f32 v[24:25], v[24:25], v[0:1] op_sel_hi:[1,0]
	v_pk_mul_f32 v[22:23], v[22:23], v[0:1] op_sel_hi:[1,0]
	v_pk_mul_f32 v[20:21], v[20:21], v[0:1] op_sel_hi:[1,0]
	v_pk_mul_f32 v[18:19], v[18:19], v[0:1] op_sel_hi:[1,0]
	v_pk_mul_f32 v[16:17], v[16:17], v[0:1] op_sel_hi:[1,0]
	v_mul_f32_e32 v193, v193, v0
	s_branch .LBB0_684

.LBB0_1022:
	ds_read_b128 v[2:5], v193
	ds_read_b128 v[6:9], v193 offset:32
	s_waitcnt lgkmcnt(1)
	v_mfma_f32_32x32x16_bf16 v[80:95], v[2:5], v[96:99], 0
	s_waitcnt lgkmcnt(0)
	v_mfma_f32_32x32x16_bf16 v[80:95], v[6:9], v[100:103], v[80:95]
	ds_read_b128 v[2:5], v193 offset:64
	ds_read_b128 v[6:9], v193 offset:96
	s_waitcnt lgkmcnt(1)
	v_mfma_f32_32x32x16_bf16 v[80:95], v[2:5], v[104:107], v[80:95]
	s_waitcnt lgkmcnt(0)
	v_mfma_f32_32x32x16_bf16 v[80:95], v[6:9], v[108:111], v[80:95]
	s_nop 11
	v_max_f32_e32 v1, v80, v81
	v_max3_f32 v1, v1, v82, v83
	v_max3_f32 v1, v1, v84, v85
	v_max3_f32 v1, v1, v86, v87
	v_max3_f32 v1, v1, v88, v89
	v_max3_f32 v1, v1, v90, v91
	v_max3_f32 v1, v1, v92, v93
	v_max3_f32 v1, v1, v94, v95
	v_mov_b32_e32 v2, v1
	s_nop 1
	v_permlane32_swap_b32_e32 v2, v1
	v_max_f32_e32 v1, v1, v2
	v_mul_f32_e32 v1, 0x3e38aa3b, v1
	v_add_f32_e32 v250, 0xc1000000, v1
	v_cmp_gt_f32_e32 vcc, v250, v180
	s_cbranch_vccz .LBB0_1024
	v_max_f32_e32 v1, v1, v1
	v_max_f32_e32 v2, v180, v180
	v_max_f32_e32 v1, v2, v1
	v_sub_f32_e32 v2, v180, v1
	v_exp_f32_e32 v2, v2
	v_mov_b32_e32 v180, v1
	v_pk_mul_f32 v[78:79], v[78:79], v[2:3] op_sel_hi:[1,0]
	v_pk_mul_f32 v[76:77], v[76:77], v[2:3] op_sel_hi:[1,0]
	v_pk_mul_f32 v[74:75], v[74:75], v[2:3] op_sel_hi:[1,0]
	v_pk_mul_f32 v[72:73], v[72:73], v[2:3] op_sel_hi:[1,0]
	v_pk_mul_f32 v[70:71], v[70:71], v[2:3] op_sel_hi:[1,0]
	v_pk_mul_f32 v[68:69], v[68:69], v[2:3] op_sel_hi:[1,0]
	v_pk_mul_f32 v[66:67], v[66:67], v[2:3] op_sel_hi:[1,0]
	v_pk_mul_f32 v[64:65], v[64:65], v[2:3] op_sel_hi:[1,0]
	v_pk_mul_f32 v[62:63], v[62:63], v[2:3] op_sel_hi:[1,0]
	v_pk_mul_f32 v[60:61], v[60:61], v[2:3] op_sel_hi:[1,0]
	v_pk_mul_f32 v[58:59], v[58:59], v[2:3] op_sel_hi:[1,0]
	v_pk_mul_f32 v[56:57], v[56:57], v[2:3] op_sel_hi:[1,0]
	v_pk_mul_f32 v[54:55], v[54:55], v[2:3] op_sel_hi:[1,0]
	v_pk_mul_f32 v[52:53], v[52:53], v[2:3] op_sel_hi:[1,0]
	v_pk_mul_f32 v[50:51], v[50:51], v[2:3] op_sel_hi:[1,0]
	v_pk_mul_f32 v[48:49], v[48:49], v[2:3] op_sel_hi:[1,0]
	v_pk_mul_f32 v[46:47], v[46:47], v[2:3] op_sel_hi:[1,0]
	v_pk_mul_f32 v[44:45], v[44:45], v[2:3] op_sel_hi:[1,0]
	v_pk_mul_f32 v[42:43], v[42:43], v[2:3] op_sel_hi:[1,0]
	v_pk_mul_f32 v[40:41], v[40:41], v[2:3] op_sel_hi:[1,0]
	v_pk_mul_f32 v[38:39], v[38:39], v[2:3] op_sel_hi:[1,0]
	v_pk_mul_f32 v[36:37], v[36:37], v[2:3] op_sel_hi:[1,0]
	v_pk_mul_f32 v[34:35], v[34:35], v[2:3] op_sel_hi:[1,0]
	v_pk_mul_f32 v[32:33], v[32:33], v[2:3] op_sel_hi:[1,0]
	v_pk_mul_f32 v[30:31], v[30:31], v[2:3] op_sel_hi:[1,0]
	v_pk_mul_f32 v[28:29], v[28:29], v[2:3] op_sel_hi:[1,0]
	v_pk_mul_f32 v[26:27], v[26:27], v[2:3] op_sel_hi:[1,0]
	v_pk_mul_f32 v[24:25], v[24:25], v[2:3] op_sel_hi:[1,0]
	v_pk_mul_f32 v[22:23], v[22:23], v[2:3] op_sel_hi:[1,0]
	v_pk_mul_f32 v[20:21], v[20:21], v[2:3] op_sel_hi:[1,0]
	v_pk_mul_f32 v[18:19], v[18:19], v[2:3] op_sel_hi:[1,0]
	v_pk_mul_f32 v[16:17], v[16:17], v[2:3] op_sel_hi:[1,0]
	v_mul_f32_e32 v196, v196, v2

.LBB0_1297:
	s_barrier
	s_waitcnt vmcnt(3)
	ds_write_b128 v166, v[112:115]
	s_waitcnt vmcnt(2)
	ds_write_b128 v166, v[116:119] offset:4352
	s_waitcnt vmcnt(1)
	ds_write_b128 v166, v[120:123] offset:8704
	s_waitcnt vmcnt(0)
	ds_write_b128 v166, v[124:127] offset:13056
	s_waitcnt vmcnt(1)
	ds_write_b128 v167, v[140:143] offset:17408
	ds_write_b128 v167, v[132:135] offset:22016
	ds_write_b128 v167, v[128:131] offset:26624
	s_waitcnt vmcnt(0)
	ds_write_b128 v167, v[136:139] offset:31232
	s_waitcnt lgkmcnt(0)
	s_barrier
	ds_read_b128 v[64:67], v170
	ds_read_b128 v[112:115], v170 offset:32
	s_waitcnt lgkmcnt(1)
	v_mfma_f32_32x32x16_bf16 v[64:79], v[64:67], v[108:111], 0
	v_lshl_add_u64 v[124:125], s[14:15], 0, v[162:163]
	v_add_co_u32_e32 v178, vcc, s37, v124
	v_lshl_add_u64 v[126:127], s[14:15], 0, v[154:155]
	s_nop 0
	v_addc_co_u32_e32 v179, vcc, 0, v125, vcc
	v_add_co_u32_e32 v180, vcc, s38, v124
	s_waitcnt lgkmcnt(0)
	v_mfma_f32_32x32x16_bf16 v[64:79], v[112:115], v[104:107], v[64:79]
	ds_read_b128 v[112:115], v170 offset:64
	ds_read_b128 v[116:119], v170 offset:96
	v_lshl_add_u64 v[128:129], s[14:15], 0, v[156:157]
	v_lshl_add_u64 v[130:131], s[14:15], 0, v[158:159]
	v_lshl_add_u64 v[136:137], s[14:15], 0, v[160:161]
	v_addc_co_u32_e32 v181, vcc, 0, v125, vcc
	v_add_co_u32_e32 v182, vcc, s39, v124
	s_waitcnt lgkmcnt(1)
	v_mfma_f32_32x32x16_bf16 v[64:79], v[112:115], v[100:103], v[64:79]
	ds_read_b128 v[112:115], v170 offset:128
	v_addc_co_u32_e32 v183, vcc, 0, v125, vcc
	v_add_co_u32_e32 v124, vcc, s40, v124
	s_nop 1
	v_addc_co_u32_e32 v125, vcc, 0, v125, vcc
	s_waitcnt lgkmcnt(1)
	v_mfma_f32_32x32x16_bf16 v[64:79], v[116:119], v[96:99], v[64:79]
	ds_read_b128 v[116:119], v170 offset:160
	ds_read_b128 v[120:123], v170 offset:192
	ds_read_b128 v[174:177], v170 offset:224
	s_waitcnt lgkmcnt(3)
	v_mfma_f32_32x32x16_bf16 v[64:79], v[112:115], v[92:95], v[64:79]
	s_waitcnt lgkmcnt(2)
	v_mfma_f32_32x32x16_bf16 v[64:79], v[116:119], v[88:91], v[64:79]
	global_load_dwordx4 v[140:143], v[126:127], off
	global_load_dwordx4 v[132:135], v[128:129], off
	s_nop 0
	global_load_dwordx4 v[128:131], v[130:131], off
	s_nop 0
	global_load_dwordx4 v[136:139], v[136:137], off
	s_nop 0
	global_load_dwordx4 v[112:115], v[178:179], off
	global_load_dwordx4 v[116:119], v[180:181], off
	s_waitcnt lgkmcnt(1)
	v_mfma_f32_32x32x16_bf16 v[64:79], v[120:123], v[84:87], v[64:79]
	global_load_dwordx4 v[120:123], v[182:183], off
	s_nop 0
	global_load_dwordx4 v[124:127], v[124:125], off
	s_waitcnt lgkmcnt(0)
	v_mfma_f32_32x32x16_bf16 v[64:79], v[174:177], v[80:83], v[64:79]
	s_nop 11
	v_max_f32_e32 v152, v64, v65
	v_max3_f32 v152, v152, v66, v67
	v_max3_f32 v152, v152, v68, v69
	v_max3_f32 v152, v152, v70, v71
	v_max3_f32 v152, v152, v72, v73
	v_max3_f32 v152, v152, v74, v75
	v_max3_f32 v152, v152, v76, v77
	v_max3_f32 v152, v152, v78, v79
	v_mov_b32_e32 v173, v152
	s_nop 1
	v_permlane32_swap_b32_e32 v173, v152
	v_max_f32_e32 v152, v152, v173
	v_mul_f32_e32 v152, 0x3e0293ee, v152
	v_add_f32_e32 v250, 0xc1000000, v152
	v_cmp_gt_f32_e32 vcc, v250, v153
	s_cbranch_vccz .LBB0_1299
	v_max_f32_e32 v152, v152, v152
	v_max_f32_e32 v173, v153, v153
	v_max_f32_e32 v173, v173, v152
	v_sub_f32_e32 v152, v153, v173
	v_exp_f32_e32 v152, v152
	s_nop 0
	v_pk_mul_f32 v[62:63], v[62:63], v[152:153] op_sel_hi:[1,0]
	v_pk_mul_f32 v[60:61], v[60:61], v[152:153] op_sel_hi:[1,0]
	v_pk_mul_f32 v[58:59], v[58:59], v[152:153] op_sel_hi:[1,0]
	v_pk_mul_f32 v[56:57], v[56:57], v[152:153] op_sel_hi:[1,0]
	v_pk_mul_f32 v[54:55], v[54:55], v[152:153] op_sel_hi:[1,0]
	v_pk_mul_f32 v[52:53], v[52:53], v[152:153] op_sel_hi:[1,0]
	v_pk_mul_f32 v[50:51], v[50:51], v[152:153] op_sel_hi:[1,0]
	v_pk_mul_f32 v[48:49], v[48:49], v[152:153] op_sel_hi:[1,0]
	v_pk_mul_f32 v[46:47], v[46:47], v[152:153] op_sel_hi:[1,0]
	v_pk_mul_f32 v[44:45], v[44:45], v[152:153] op_sel_hi:[1,0]
	v_pk_mul_f32 v[42:43], v[42:43], v[152:153] op_sel_hi:[1,0]
	v_pk_mul_f32 v[40:41], v[40:41], v[152:153] op_sel_hi:[1,0]
	v_pk_mul_f32 v[38:39], v[38:39], v[152:153] op_sel_hi:[1,0]
	v_pk_mul_f32 v[36:37], v[36:37], v[152:153] op_sel_hi:[1,0]
	v_pk_mul_f32 v[34:35], v[34:35], v[152:153] op_sel_hi:[1,0]
	v_pk_mul_f32 v[32:33], v[32:33], v[152:153] op_sel_hi:[1,0]
	v_pk_mul_f32 v[30:31], v[30:31], v[152:153] op_sel_hi:[1,0]
	v_pk_mul_f32 v[28:29], v[28:29], v[152:153] op_sel_hi:[1,0]
	v_pk_mul_f32 v[26:27], v[26:27], v[152:153] op_sel_hi:[1,0]
	v_pk_mul_f32 v[24:25], v[24:25], v[152:153] op_sel_hi:[1,0]
	v_pk_mul_f32 v[22:23], v[22:23], v[152:153] op_sel_hi:[1,0]
	v_pk_mul_f32 v[20:21], v[20:21], v[152:153] op_sel_hi:[1,0]
	v_pk_mul_f32 v[18:19], v[18:19], v[152:153] op_sel_hi:[1,0]
	v_pk_mul_f32 v[16:17], v[16:17], v[152:153] op_sel_hi:[1,0]
	v_pk_mul_f32 v[14:15], v[14:15], v[152:153] op_sel_hi:[1,0]
	v_pk_mul_f32 v[12:13], v[12:13], v[152:153] op_sel_hi:[1,0]
	v_pk_mul_f32 v[10:11], v[10:11], v[152:153] op_sel_hi:[1,0]
	v_pk_mul_f32 v[8:9], v[8:9], v[152:153] op_sel_hi:[1,0]
	v_pk_mul_f32 v[6:7], v[6:7], v[152:153] op_sel_hi:[1,0]
	v_pk_mul_f32 v[4:5], v[4:5], v[152:153] op_sel_hi:[1,0]
	v_pk_mul_f32 v[2:3], v[2:3], v[152:153] op_sel_hi:[1,0]
	v_pk_mul_f32 v[0:1], v[0:1], v[152:153] op_sel_hi:[1,0]
	v_mul_f32_e32 v172, v172, v152
	v_mov_b32_e32 v153, v173
.LBB0_1299:
	v_mov_b32_e32 v152, v153
	v_pk_fma_f32 v[64:65], v[64:65], s[18:19], v[152:153] op_sel_hi:[1,0,0] neg_lo:[0,0,1] neg_hi:[0,0,1]
	v_pk_fma_f32 v[72:73], v[72:73], s[18:19], v[152:153] op_sel_hi:[1,0,0] neg_lo:[0,0,1] neg_hi:[0,0,1]
	v_exp_f32_e32 v202, v64
	v_exp_f32_e32 v203, v65
	v_pk_fma_f32 v[64:65], v[66:67], s[18:19], v[152:153] op_sel_hi:[1,0,0] neg_lo:[0,0,1] neg_hi:[0,0,1]
	ds_read_b128 v[174:177], v171 offset:17440
	v_exp_f32_e32 v204, v64
	v_exp_f32_e32 v205, v65
	v_pk_fma_f32 v[64:65], v[68:69], s[18:19], v[152:153] op_sel_hi:[1,0,0] neg_lo:[0,0,1] neg_hi:[0,0,1]
	v_pk_fma_f32 v[68:69], v[70:71], s[18:19], v[152:153] op_sel_hi:[1,0,0] neg_lo:[0,0,1] neg_hi:[0,0,1]
	v_exp_f32_e32 v206, v64
	v_exp_f32_e32 v207, v65
	ds_read_b128 v[64:67], v171 offset:17408
	v_exp_f32_e32 v208, v68
	v_exp_f32_e32 v209, v69
	v_cvt_pk_bf16_f32 v68, v202, v203
	v_cvt_pk_bf16_f32 v69, v204, v205
	v_cvt_pk_bf16_f32 v70, v206, v207
	v_cvt_pk_bf16_f32 v71, v208, v209
	v_exp_f32_e32 v210, v72
	v_exp_f32_e32 v211, v73
	s_waitcnt lgkmcnt(0)
	v_mfma_f32_32x32x16_bf16 v[48:63], v[64:67], v[68:71], v[48:63]
	ds_read_b128 v[64:67], v171 offset:22016
	ds_read_b128 v[178:181], v171 offset:22048
	s_waitcnt lgkmcnt(1)
	v_mfma_f32_32x32x16_bf16 v[32:47], v[64:67], v[68:71], v[32:47]
	ds_read_b128 v[64:67], v171 offset:26624
	ds_read_b128 v[182:185], v171 offset:31232
	ds_read_b128 v[186:189], v171 offset:26656
	ds_read_b128 v[190:193], v171 offset:31264
	s_waitcnt lgkmcnt(3)
	v_mfma_f32_32x32x16_bf16 v[16:31], v[64:67], v[68:71], v[16:31]
	v_fma_f32 v64, v74, s18, -v152
	v_fma_f32 v65, v75, s18, -v152
	v_exp_f32_e32 v212, v64
	v_exp_f32_e32 v213, v65
	v_pk_fma_f32 v[64:65], v[76:77], s[18:19], v[152:153] op_sel_hi:[1,0,0] neg_lo:[0,0,1] neg_hi:[0,0,1]
	s_nop 0
	v_exp_f32_e32 v214, v64
	v_exp_f32_e32 v215, v65
	v_pk_fma_f32 v[64:65], v[78:79], s[18:19], v[152:153] op_sel_hi:[1,0,0] neg_lo:[0,0,1] neg_hi:[0,0,1]
	s_waitcnt lgkmcnt(2)
	v_mfma_f32_32x32x16_bf16 v[0:15], v[182:185], v[68:71], v[0:15]
	v_exp_f32_e32 v216, v64
	v_exp_f32_e32 v217, v65
	v_cvt_pk_bf16_f32 v182, v210, v211
	v_cvt_pk_bf16_f32 v183, v212, v213
	v_cvt_pk_bf16_f32 v184, v214, v215
	v_cvt_pk_bf16_f32 v185, v216, v217
	s_nop 1
	v_mfma_f32_32x32x16_bf16 v[48:63], v[174:177], v[182:185], v[48:63]
	ds_read_b128 v[64:67], v170 offset:8704
	ds_read_b128 v[174:177], v170 offset:8736
	s_waitcnt lgkmcnt(1)
	v_mfma_f32_32x32x16_bf16 v[64:79], v[64:67], v[108:111], 0
	s_waitcnt lgkmcnt(0)
	v_mfma_f32_32x32x16_bf16 v[64:79], v[174:177], v[104:107], v[64:79]
	ds_read_b128 v[174:177], v170 offset:8768
	ds_read_b128 v[194:197], v170 offset:8800
	s_waitcnt lgkmcnt(1)
	v_mfma_f32_32x32x16_bf16 v[64:79], v[174:177], v[100:103], v[64:79]
	s_waitcnt lgkmcnt(0)
	v_mfma_f32_32x32x16_bf16 v[64:79], v[194:197], v[96:99], v[64:79]
	ds_read_b128 v[174:177], v170 offset:8832
	ds_read_b128 v[194:197], v170 offset:8864
	s_waitcnt lgkmcnt(1)
	v_mfma_f32_32x32x16_bf16 v[64:79], v[174:177], v[92:95], v[64:79]
	s_waitcnt lgkmcnt(0)
	v_mfma_f32_32x32x16_bf16 v[64:79], v[194:197], v[88:91], v[64:79]
	ds_read_b128 v[174:177], v170 offset:8896
	ds_read_b128 v[194:197], v170 offset:8928
	s_waitcnt lgkmcnt(1)
	v_mfma_f32_32x32x16_bf16 v[64:79], v[174:177], v[84:87], v[64:79]
	v_add_f32_e64 v174, v204, v202
	v_add_f32_e64 v175, v205, v203
	v_add_f32_e64 v174, v206, v174
	v_add_f32_e64 v175, v207, v175
	v_pk_add_f32 v[174:175], v[208:209], v[174:175]
	s_waitcnt lgkmcnt(0)
	v_mfma_f32_32x32x16_bf16 v[64:79], v[194:197], v[80:83], v[64:79]
	v_add_f32_e64 v174, v210, v174
	v_add_f32_e64 v175, v211, v175
	v_add_f32_e64 v174, v212, v174
	v_add_f32_e64 v175, v213, v175
	v_add_f32_e64 v174, v214, v174
	v_add_f32_e64 v175, v215, v175
	s_nop 5
	v_max_f32_e32 v152, v64, v65
	v_max3_f32 v152, v152, v66, v67
	v_max3_f32 v152, v152, v68, v69
	v_max3_f32 v152, v152, v70, v71
	v_max3_f32 v152, v152, v72, v73
	v_max3_f32 v152, v152, v74, v75
	v_max3_f32 v152, v152, v76, v77
	v_max3_f32 v152, v152, v78, v79
	v_mov_b32_e32 v173, v152
	s_nop 1
	v_permlane32_swap_b32_e32 v173, v152
	v_mfma_f32_32x32x16_bf16 v[32:47], v[178:181], v[182:185], v[32:47]
	v_add_f32_e64 v174, v216, v174
	v_add_f32_e64 v175, v217, v175
	v_max_f32_e32 v173, v173, v173
	v_max_f32_e32 v152, v152, v173
	v_add_f32_e32 v174, v174, v175
	v_mul_f32_e32 v152, 0x3e0293ee, v152
	v_mfma_f32_32x32x16_bf16 v[16:31], v[186:189], v[182:185], v[16:31]
	v_add_f32_e32 v172, v172, v174
	v_add_f32_e32 v250, 0xc1000000, v152
	v_cmp_gt_f32_e32 vcc, v250, v153
	v_mfma_f32_32x32x16_bf16 v[0:15], v[190:193], v[182:185], v[0:15]
	s_cbranch_vccnz .LBB0_1295
	v_mov_b32_e32 v152, v153
	s_branch .LBB0_1296
.LBB0_1301:
	s_barrier
	s_waitcnt vmcnt(3)
	ds_write_b128 v166, v[112:115]
	s_waitcnt vmcnt(2)
	ds_write_b128 v166, v[116:119] offset:4352
	s_waitcnt vmcnt(1)
	ds_write_b128 v166, v[120:123] offset:8704
	s_waitcnt vmcnt(0)
	ds_write_b128 v166, v[124:127] offset:13056
	ds_write_b128 v167, v[140:143] offset:17408
	ds_write_b128 v167, v[132:135] offset:22016
	ds_write_b128 v167, v[128:131] offset:26624
	ds_write_b128 v167, v[136:139] offset:31232
	s_waitcnt lgkmcnt(0)
	s_barrier
	ds_read_b128 v[64:67], v170
	ds_read_b128 v[112:115], v170 offset:32
	s_waitcnt lgkmcnt(1)
	v_mfma_f32_32x32x16_bf16 v[64:79], v[64:67], v[108:111], 0
	s_waitcnt lgkmcnt(0)
	v_mfma_f32_32x32x16_bf16 v[64:79], v[112:115], v[104:107], v[64:79]
	ds_read_b128 v[112:115], v170 offset:64
	ds_read_b128 v[116:119], v170 offset:96
	s_waitcnt lgkmcnt(1)
	v_mfma_f32_32x32x16_bf16 v[64:79], v[112:115], v[100:103], v[64:79]
	s_waitcnt lgkmcnt(0)
	v_mfma_f32_32x32x16_bf16 v[64:79], v[116:119], v[96:99], v[64:79]
	ds_read_b128 v[112:115], v170 offset:128
	ds_read_b128 v[116:119], v170 offset:160
	s_waitcnt lgkmcnt(1)
	v_mfma_f32_32x32x16_bf16 v[64:79], v[112:115], v[92:95], v[64:79]
	s_waitcnt lgkmcnt(0)
	v_mfma_f32_32x32x16_bf16 v[64:79], v[116:119], v[88:91], v[64:79]
	ds_read_b128 v[112:115], v170 offset:192
	ds_read_b128 v[116:119], v170 offset:224
	s_waitcnt lgkmcnt(1)
	v_mfma_f32_32x32x16_bf16 v[64:79], v[112:115], v[84:87], v[64:79]
	s_waitcnt lgkmcnt(0)
	v_mfma_f32_32x32x16_bf16 v[64:79], v[116:119], v[80:83], v[64:79]
	s_nop 11
	v_max_f32_e32 v112, v64, v65
	v_max3_f32 v112, v112, v66, v67
	v_max3_f32 v112, v112, v68, v69
	v_max3_f32 v112, v112, v70, v71
	v_max3_f32 v112, v112, v72, v73
	v_max3_f32 v112, v112, v74, v75
	v_max3_f32 v112, v112, v76, v77
	v_max3_f32 v112, v112, v78, v79
	v_mov_b32_e32 v113, v112
	s_nop 1
	v_permlane32_swap_b32_e32 v113, v112
	v_max_f32_e32 v112, v112, v113
	v_mul_f32_e32 v112, 0x3e0293ee, v112
	v_add_f32_e32 v250, 0xc1000000, v112
	v_cmp_gt_f32_e32 vcc, v250, v153
	s_cbranch_vccz .LBB0_1303
	v_max_f32_e32 v112, v112, v112
	v_max_f32_e32 v113, v153, v153
	v_max_f32_e32 v152, v113, v112
	v_sub_f32_e32 v112, v153, v152
	v_exp_f32_e32 v112, v112
	v_mov_b32_e32 v153, v152
	v_pk_mul_f32 v[62:63], v[62:63], v[112:113] op_sel_hi:[1,0]
	v_pk_mul_f32 v[60:61], v[60:61], v[112:113] op_sel_hi:[1,0]
	v_pk_mul_f32 v[58:59], v[58:59], v[112:113] op_sel_hi:[1,0]
	v_pk_mul_f32 v[56:57], v[56:57], v[112:113] op_sel_hi:[1,0]
	v_pk_mul_f32 v[54:55], v[54:55], v[112:113] op_sel_hi:[1,0]
	v_pk_mul_f32 v[52:53], v[52:53], v[112:113] op_sel_hi:[1,0]
	v_pk_mul_f32 v[50:51], v[50:51], v[112:113] op_sel_hi:[1,0]
	v_pk_mul_f32 v[48:49], v[48:49], v[112:113] op_sel_hi:[1,0]
	v_pk_mul_f32 v[46:47], v[46:47], v[112:113] op_sel_hi:[1,0]
	v_pk_mul_f32 v[44:45], v[44:45], v[112:113] op_sel_hi:[1,0]
	v_pk_mul_f32 v[42:43], v[42:43], v[112:113] op_sel_hi:[1,0]
	v_pk_mul_f32 v[40:41], v[40:41], v[112:113] op_sel_hi:[1,0]
	v_pk_mul_f32 v[38:39], v[38:39], v[112:113] op_sel_hi:[1,0]
	v_pk_mul_f32 v[36:37], v[36:37], v[112:113] op_sel_hi:[1,0]
	v_pk_mul_f32 v[34:35], v[34:35], v[112:113] op_sel_hi:[1,0]
	v_pk_mul_f32 v[32:33], v[32:33], v[112:113] op_sel_hi:[1,0]
	v_pk_mul_f32 v[30:31], v[30:31], v[112:113] op_sel_hi:[1,0]
	v_pk_mul_f32 v[28:29], v[28:29], v[112:113] op_sel_hi:[1,0]
	v_pk_mul_f32 v[26:27], v[26:27], v[112:113] op_sel_hi:[1,0]
	v_pk_mul_f32 v[24:25], v[24:25], v[112:113] op_sel_hi:[1,0]
	v_pk_mul_f32 v[22:23], v[22:23], v[112:113] op_sel_hi:[1,0]
	v_pk_mul_f32 v[20:21], v[20:21], v[112:113] op_sel_hi:[1,0]
	v_pk_mul_f32 v[18:19], v[18:19], v[112:113] op_sel_hi:[1,0]
	v_pk_mul_f32 v[16:17], v[16:17], v[112:113] op_sel_hi:[1,0]
	v_pk_mul_f32 v[14:15], v[14:15], v[112:113] op_sel_hi:[1,0]
	v_pk_mul_f32 v[12:13], v[12:13], v[112:113] op_sel_hi:[1,0]
	v_pk_mul_f32 v[10:11], v[10:11], v[112:113] op_sel_hi:[1,0]
	v_pk_mul_f32 v[8:9], v[8:9], v[112:113] op_sel_hi:[1,0]
	v_pk_mul_f32 v[6:7], v[6:7], v[112:113] op_sel_hi:[1,0]
	v_pk_mul_f32 v[4:5], v[4:5], v[112:113] op_sel_hi:[1,0]
	v_pk_mul_f32 v[2:3], v[2:3], v[112:113] op_sel_hi:[1,0]
	v_pk_mul_f32 v[0:1], v[0:1], v[112:113] op_sel_hi:[1,0]
	v_mul_f32_e32 v172, v172, v112
	v_mov_b32_e32 v112, v152
	s_branch .LBB0_1304
